# v29: v27 + layer-A k-loop: the LGKM wait hipcc placed after the first fragment read of every iteration (a WAW guard against the old epilogue's ds_bpermute, no longer present) removed; no back-edge rot
# speedup vs baseline: 1.0091x; 1.0091x over previous
.LBB0_446:
	s_add_u32 s28, s0, 0xfffc0080
	s_addc_u32 s29, s1, -1
	s_add_i32 s52, 16, 0x10000
	s_cmp_eq_u32 s51, 12
	s_cselect_b32 s31, s3, s29
	s_cselect_b32 s30, s23, s28
	v_add_u32_e32 v3, s52, v175
	s_cselect_b32 s29, s21, s50
	s_cselect_b32 s28, s48, s49
	s_add_i32 s54, 16, 0x14000
	ds_read_b128 v[142:145], v3
	ds_read_b128 v[146:149], v3 offset:1024
	ds_read_b128 v[150:153], v3 offset:2048
	ds_read_b128 v[154:157], v3 offset:3072
	v_add_u32_e32 v3, s54, v175
	ds_read_b128 v[158:161], v3
	ds_read_b128 v[162:165], v3 offset:1024
	ds_read_b128 v[166:169], v3 offset:2048
	ds_read_b128 v[170:173], v3 offset:3072
	v_lshl_add_u64 v[210:211], s[0:1], 0, v[138:139]
	s_add_i32 m0, s39, 0xc000
	ds_read_b128 v[178:181], v177
	ds_read_b128 v[182:185], v177 offset:1024
	ds_read_b128 v[186:189], v177 offset:2048
	ds_read_b128 v[190:193], v177 offset:3072
	ds_read_b128 v[194:197], v177 offset:4096
	ds_read_b128 v[198:201], v177 offset:5120
	ds_read_b128 v[202:205], v177 offset:6144
	ds_read_b128 v[206:209], v177 offset:7168
	global_load_lds_dwordx4 v[210:211], off
	v_lshl_add_u64 v[210:211], s[0:1], 0, v[140:141]
	s_add_i32 m0, s39, 0xe000
	s_nop 0
	global_load_lds_dwordx4 v[210:211], off
	s_waitcnt vmcnt(8)
	s_waitcnt lgkmcnt(0)
	s_barrier
	s_setprio 1
	s_waitcnt lgkmcnt(0)
	v_mfma_f32_16x16x32_bf16 v[128:131], v[142:145], v[178:181], v[128:131]
	v_mfma_f32_16x16x32_bf16 v[120:123], v[150:153], v[178:181], v[120:123]
	v_mfma_f32_16x16x32_bf16 v[112:115], v[142:145], v[186:189], v[112:115]
	v_mfma_f32_16x16x32_bf16 v[104:107], v[150:153], v[186:189], v[104:107]
	v_mfma_f32_16x16x32_bf16 v[96:99], v[142:145], v[194:197], v[96:99]
	v_mfma_f32_16x16x32_bf16 v[88:91], v[150:153], v[194:197], v[88:91]
	v_mfma_f32_16x16x32_bf16 v[80:83], v[142:145], v[202:205], v[80:83]
	v_mfma_f32_16x16x32_bf16 v[72:75], v[150:153], v[202:205], v[72:75]
	v_mfma_f32_16x16x32_bf16 v[128:131], v[146:149], v[182:185], v[128:131]
	v_mfma_f32_16x16x32_bf16 v[120:123], v[154:157], v[182:185], v[120:123]
	v_mfma_f32_16x16x32_bf16 v[112:115], v[146:149], v[190:193], v[112:115]
	v_mfma_f32_16x16x32_bf16 v[104:107], v[154:157], v[190:193], v[104:107]
	v_mfma_f32_16x16x32_bf16 v[96:99], v[146:149], v[198:201], v[96:99]
	v_mfma_f32_16x16x32_bf16 v[88:91], v[154:157], v[198:201], v[88:91]
	v_mfma_f32_16x16x32_bf16 v[80:83], v[146:149], v[206:209], v[80:83]
	v_mfma_f32_16x16x32_bf16 v[72:75], v[154:157], v[206:209], v[72:75]
	s_setprio 0
	s_setprio 1
	v_mfma_f32_16x16x32_bf16 v[124:127], v[158:161], v[178:181], v[124:127]
	v_mfma_f32_16x16x32_bf16 v[116:119], v[166:169], v[178:181], v[116:119]
	v_mfma_f32_16x16x32_bf16 v[108:111], v[158:161], v[186:189], v[108:111]
	v_mfma_f32_16x16x32_bf16 v[100:103], v[166:169], v[186:189], v[100:103]
	v_mfma_f32_16x16x32_bf16 v[92:95], v[158:161], v[194:197], v[92:95]
	v_mfma_f32_16x16x32_bf16 v[84:87], v[166:169], v[194:197], v[84:87]
	v_mfma_f32_16x16x32_bf16 v[76:79], v[158:161], v[202:205], v[76:79]
	v_mfma_f32_16x16x32_bf16 v[68:71], v[166:169], v[202:205], v[68:71]
	v_mfma_f32_16x16x32_bf16 v[124:127], v[162:165], v[182:185], v[124:127]
	v_mfma_f32_16x16x32_bf16 v[116:119], v[170:173], v[182:185], v[116:119]
	v_mfma_f32_16x16x32_bf16 v[108:111], v[162:165], v[190:193], v[108:111]
	v_mfma_f32_16x16x32_bf16 v[100:103], v[170:173], v[190:193], v[100:103]
	v_mfma_f32_16x16x32_bf16 v[92:95], v[162:165], v[198:201], v[92:95]
	v_mfma_f32_16x16x32_bf16 v[84:87], v[170:173], v[198:201], v[84:87]
	v_mfma_f32_16x16x32_bf16 v[76:79], v[162:165], v[206:209], v[76:79]
	v_mfma_f32_16x16x32_bf16 v[68:71], v[170:173], v[206:209], v[68:71]
	s_setprio 0
	s_barrier
	s_add_i32 s52, s52, s38
	v_lshl_add_u64 v[210:211], s[28:29], 0, v[134:135]
	s_mov_b32 m0, s52
	ds_read_b128 v[178:181], v177 offset:16384
	ds_read_b128 v[182:185], v177 offset:17408
	ds_read_b128 v[186:189], v177 offset:18432
	ds_read_b128 v[190:193], v177 offset:19456
	ds_read_b128 v[194:197], v177 offset:20480
	ds_read_b128 v[198:201], v177 offset:21504
	ds_read_b128 v[202:205], v177 offset:22528
	ds_read_b128 v[206:209], v177 offset:23552
	global_load_lds_dwordx4 v[210:211], off
	s_add_i32 m0, s52, 0x2000
	s_add_u32 s52, s28, 0x40000
	v_lshl_add_u64 v[212:213], s[28:29], 0, v[0:1]
	s_addc_u32 s53, s29, 0
	s_add_i32 s54, s54, s38
	global_load_lds_dwordx4 v[212:213], off
	v_lshl_add_u64 v[214:215], s[52:53], 0, v[134:135]
	s_mov_b32 m0, s54
	v_lshl_add_u64 v[216:217], s[30:31], 0, v[132:133]
	global_load_lds_dwordx4 v[214:215], off
	v_lshl_add_u64 v[214:215], s[52:53], 0, v[0:1]
	s_add_i32 m0, s54, 0x2000
	s_nop 0
	global_load_lds_dwordx4 v[214:215], off
	v_lshl_add_u64 v[214:215], s[30:31], 0, v[136:137]
	s_waitcnt vmcnt(6)
	s_waitcnt lgkmcnt(0)
	s_barrier
	s_setprio 1
	s_waitcnt lgkmcnt(0)
	v_mfma_f32_16x16x32_bf16 v[64:67], v[142:145], v[178:181], v[64:67]
	v_mfma_f32_16x16x32_bf16 v[56:59], v[150:153], v[178:181], v[56:59]
	v_mfma_f32_16x16x32_bf16 v[48:51], v[142:145], v[186:189], v[48:51]
	v_mfma_f32_16x16x32_bf16 v[40:43], v[150:153], v[186:189], v[40:43]
	v_mfma_f32_16x16x32_bf16 v[32:35], v[142:145], v[194:197], v[32:35]
	v_mfma_f32_16x16x32_bf16 v[24:27], v[150:153], v[194:197], v[24:27]
	v_mfma_f32_16x16x32_bf16 v[16:19], v[142:145], v[202:205], v[16:19]
	v_mfma_f32_16x16x32_bf16 v[8:11], v[150:153], v[202:205], v[8:11]
	v_mfma_f32_16x16x32_bf16 v[64:67], v[146:149], v[182:185], v[64:67]
	v_mfma_f32_16x16x32_bf16 v[56:59], v[154:157], v[182:185], v[56:59]
	v_mfma_f32_16x16x32_bf16 v[48:51], v[146:149], v[190:193], v[48:51]
	v_mfma_f32_16x16x32_bf16 v[40:43], v[154:157], v[190:193], v[40:43]
	v_mfma_f32_16x16x32_bf16 v[32:35], v[146:149], v[198:201], v[32:35]
	v_mfma_f32_16x16x32_bf16 v[24:27], v[154:157], v[198:201], v[24:27]
	v_mfma_f32_16x16x32_bf16 v[16:19], v[146:149], v[206:209], v[16:19]
	v_mfma_f32_16x16x32_bf16 v[8:11], v[154:157], v[206:209], v[8:11]
	s_setprio 0
	s_setprio 1
	v_mfma_f32_16x16x32_bf16 v[60:63], v[158:161], v[178:181], v[60:63]
	v_mfma_f32_16x16x32_bf16 v[52:55], v[166:169], v[178:181], v[52:55]
	v_mfma_f32_16x16x32_bf16 v[44:47], v[158:161], v[186:189], v[44:47]
	v_mfma_f32_16x16x32_bf16 v[36:39], v[166:169], v[186:189], v[36:39]
	v_mfma_f32_16x16x32_bf16 v[28:31], v[158:161], v[194:197], v[28:31]
	v_mfma_f32_16x16x32_bf16 v[20:23], v[166:169], v[194:197], v[20:23]
	v_mfma_f32_16x16x32_bf16 v[12:15], v[158:161], v[202:205], v[12:15]
	v_mfma_f32_16x16x32_bf16 v[4:7], v[166:169], v[202:205], v[4:7]
	v_mfma_f32_16x16x32_bf16 v[60:63], v[162:165], v[182:185], v[60:63]
	v_mfma_f32_16x16x32_bf16 v[52:55], v[170:173], v[182:185], v[52:55]
	v_mfma_f32_16x16x32_bf16 v[44:47], v[162:165], v[190:193], v[44:47]
	v_mfma_f32_16x16x32_bf16 v[36:39], v[170:173], v[190:193], v[36:39]
	v_mfma_f32_16x16x32_bf16 v[28:31], v[162:165], v[198:201], v[28:31]
	v_mfma_f32_16x16x32_bf16 v[20:23], v[170:173], v[198:201], v[20:23]
	v_mfma_f32_16x16x32_bf16 v[12:15], v[162:165], v[206:209], v[12:15]
	v_mfma_f32_16x16x32_bf16 v[4:7], v[170:173], v[206:209], v[4:7]
	s_setprio 0
	s_barrier
